# read-once loads non-temporal in merge, gMLP unit loads and layer-0 out-proj f32 x loads
# baseline (speedup 1.0000x reference)
; __device__ __forceinline__ float bflo(unsigned u) { return __uint_as_float(u << 16); }
; __device__ __forceinline__ float bfhi(unsigned u) { return __uint_as_float(u & 0xffff0000u); }
; __device__ __forceinline__ unsigned pk2(float lo, float hi) { f32x2_t v = {lo, hi}; bf16x2_t b = __builtin_convertvector(v, bf16x2_t); return __builtin_bit_cast(unsigned, b); }
; __global__ void __launch_bounds__(NTHREADS, 2) fwd_megakernel(Args A) {
;     ...
;                 for (int i = bx * NTHREADS + tid; i < 8192 * 128; i += G * NTHREADS) {
;                     const int row = i >> 7, o8 = i & 127, h = o8 >> 3;
;                     const float l0 = LSE[((size_t)0 * 8192 + row) * 16 + h], l1 = LSE[((size_t)1 * 8192 + row) * 16 + h], l2 = LSE[((size_t)2 * 8192 + row) * 16 + h];
;                     const float mx = fmaxf(l0, fmaxf(l1, l2)); const float e0 = __expf(l0 - mx), e1 = __expf(l1 - mx), e2 = __expf(l2 - mx); const float inv = 1.f / (e0 + e1 + e2);
;                     const float w0 = e0 * inv, w1 = e1 * inv, w2 = e2 * inv;
;                     const size_t off = (size_t)row * DM + 8 * o8;
;                     const v4u a = *(const v4u*)(OG0 + off), b = *(const v4u*)(OG1 + off), c = *(const v4u*)(OG2 + off);
;                     v4u o;
;                     o.x = pk2(w0 * bflo(a.x) + w1 * bflo(b.x) + w2 * bflo(c.x), w0 * bfhi(a.x) + w1 * bfhi(b.x) + w2 * bfhi(c.x));
;                     o.y = pk2(w0 * bflo(a.y) + w1 * bflo(b.y) + w2 * bflo(c.y), w0 * bfhi(a.y) + w1 * bfhi(b.y) + w2 * bfhi(c.y));
;                     o.z = pk2(w0 * bflo(a.z) + w1 * bflo(b.z) + w2 * bflo(c.z), w0 * bfhi(a.z) + w1 * bfhi(b.z) + w2 * bfhi(c.z));
;                     o.w = pk2(w0 * bflo(a.w) + w1 * bflo(b.w) + w2 * bflo(c.w), w0 * bfhi(a.w) + w1 * bfhi(b.w) + w2 * bfhi(c.w));
;                     *(v4u*)(Y + (size_t)row_base * DM + off) = o;
;                 }
.LBB0_403:
	s_waitcnt vmcnt(3)
	v_ashrrev_i32_e32 v4, 7, v1
	v_ashrrev_i32_e32 v5, 31, v4
	v_lshlrev_b64 v[2:3], 6, v[4:5]
	v_lshl_add_u64 v[2:3], s[6:7], 0, v[2:3]
	v_mov_b32_e32 v147, v0
	v_lshl_add_u64 v[2:3], v[2:3], 0, v[146:147]
	v_add_co_u32_e32 v6, vcc, 0x80000, v2
	global_load_dword v8, v[2:3], off nt
	s_nop 0
	v_addc_co_u32_e32 v7, vcc, 0, v3, vcc
	global_load_dword v6, v[6:7], off nt
	v_add_co_u32_e32 v2, vcc, s21, v2
	v_lshlrev_b64 v[20:21], 11, v[4:5]
	s_nop 0
	v_addc_co_u32_e32 v3, vcc, 0, v3, vcc
	global_load_dword v2, v[2:3], off nt
	v_lshl_or_b32 v20, v144, 1, v20
	s_waitcnt vmcnt(5)
	v_lshl_add_u64 v[12:13], s[24:25], 0, v[20:21]
	global_load_dwordx4 v[12:15], v[12:13], off nt
	v_lshl_add_u64 v[4:5], s[80:81], 0, v[20:21]
	v_lshl_add_u64 v[26:27], s[8:9], 0, v[20:21]
	global_load_dwordx4 v[30:33], v[4:5], off nt
	global_load_dwordx4 v[34:37], v[26:27], off nt
	v_add_u32_e32 v1, s20, v1
	s_waitcnt vmcnt(3)
	v_max3_f32 v3, v8, v6, v2
	v_sub_f32_e32 v7, v8, v3
	v_sub_f32_e32 v6, v6, v3
	v_mul_f32_e32 v7, 0x3fb8aa3b, v7
	v_mul_f32_e32 v6, 0x3fb8aa3b, v6
	v_sub_f32_e32 v2, v2, v3
	v_exp_f32_e32 v17, v7
	v_exp_f32_e32 v16, v6
	v_mul_f32_e32 v2, 0x3fb8aa3b, v2
	v_exp_f32_e32 v2, v2
	s_waitcnt vmcnt(2)
	v_lshlrev_b32_e32 v24, 16, v12
	v_add_f32_e32 v3, v17, v16
	v_and_b32_e32 v25, 0xffff0000, v12
	v_add_f32_e32 v3, v2, v3
	v_div_scale_f32 v6, s[4:5], v3, v3, 1.0
	v_rcp_f32_e32 v7, v6
	v_lshlrev_b32_e32 v12, 16, v13
	v_and_b32_e32 v13, 0xffff0000, v13
	s_mov_b32 s4, 0xfffff
	v_fma_f32 v8, -v6, v7, 1.0
	v_fmac_f32_e32 v7, v8, v7
	v_div_scale_f32 v8, vcc, 1.0, v3, 1.0
	v_mul_f32_e32 v9, v8, v7
	v_fma_f32 v10, -v6, v9, v8
	v_fmac_f32_e32 v9, v10, v7
	v_fma_f32 v6, -v6, v9, v8
	v_div_fmas_f32 v6, v6, v7, v9
	v_div_fixup_f32 v18, v6, v3, 1.0
	v_pk_mul_f32 v[16:17], v[16:17], v[18:19] op_sel_hi:[1,0]
	v_mul_f32_e32 v2, v2, v18
	v_cmp_lt_i32_e32 vcc, s4, v1
	s_or_b64 s[2:3], vcc, s[2:3]
	s_waitcnt vmcnt(1)
	v_lshlrev_b32_e32 v22, 16, v30
	v_and_b32_e32 v19, 0xffff0000, v30
	s_waitcnt vmcnt(0)
	v_and_b32_e32 v23, 0xffff0000, v34
	v_lshlrev_b32_e32 v18, 16, v34
	v_pk_mul_f32 v[22:23], v[16:17], v[22:23] op_sel:[1,0] op_sel_hi:[0,1]
	v_pk_fma_f32 v[18:19], v[16:17], v[18:19], v[22:23]
	v_lshlrev_b32_e32 v34, 16, v31
	v_pk_fma_f32 v[18:19], v[2:3], v[24:25], v[18:19] op_sel_hi:[0,1,1]
	v_cvt_pk_bf16_f32 v30, v18, v19
	v_lshlrev_b32_e32 v18, 16, v35
	v_and_b32_e32 v35, 0xffff0000, v35
	v_and_b32_e32 v19, 0xffff0000, v31
	v_pk_mul_f32 v[34:35], v[16:17], v[34:35] op_sel:[1,0] op_sel_hi:[0,1]
	v_pk_fma_f32 v[34:35], v[16:17], v[18:19], v[34:35]
	v_lshlrev_b32_e32 v18, 16, v14
	v_pk_fma_f32 v[34:35], v[2:3], v[12:13], v[34:35] op_sel_hi:[0,1,1]
	v_lshlrev_b32_e32 v12, 16, v32
	v_and_b32_e32 v13, 0xffff0000, v36
	v_cvt_pk_bf16_f32 v31, v34, v35
	v_lshlrev_b32_e32 v34, 16, v36
	v_and_b32_e32 v35, 0xffff0000, v32
	v_pk_mul_f32 v[12:13], v[16:17], v[12:13] op_sel:[1,0] op_sel_hi:[0,1]
	v_and_b32_e32 v19, 0xffff0000, v14
	v_pk_fma_f32 v[34:35], v[16:17], v[34:35], v[12:13]
	v_lshlrev_b32_e32 v36, 16, v33
	v_pk_fma_f32 v[34:35], v[2:3], v[18:19], v[34:35] op_sel_hi:[0,1,1]
	v_cvt_pk_bf16_f32 v32, v34, v35
	v_lshlrev_b32_e32 v34, 16, v37
	v_and_b32_e32 v37, 0xffff0000, v37
	v_and_b32_e32 v35, 0xffff0000, v33
	v_pk_mul_f32 v[36:37], v[16:17], v[36:37] op_sel:[1,0] op_sel_hi:[0,1]
	v_pk_fma_f32 v[34:35], v[16:17], v[34:35], v[36:37]
	v_lshlrev_b32_e32 v36, 16, v15
	v_and_b32_e32 v37, 0xffff0000, v15
	v_pk_fma_f32 v[2:3], v[2:3], v[36:37], v[34:35] op_sel_hi:[0,1,1]
	v_cvt_pk_bf16_f32 v33, v2, v3
	v_lshl_add_u64 v[2:3], s[28:29], 0, v[20:21]
	global_store_dwordx4 v[2:3], v[30:33], off
	s_andn2_b64 exec, exec, s[2:3]
	s_cbranch_execnz .LBB0_403

; __device__ __forceinline__ void gmlp_unit(LAS unsigned char* lds, int unit, const bf16* U, const bf16* Vb, bf16* Y, const float* vs1, const float* vs2,
;                                           const float* lnw, const float* lnb, const float* bs) {
;     ...
;     v4u uu[4], gg[4];
; #pragma unroll
;     for (int j = 0; j < 4; ++j) { const size_t off = (m0 + t) * 1024 + c0 + 32 * j + 8 * g4; uu[j] = *(const v4u*)(U + off); gg[j] = *(const v4u*)(Y + off); }
;     {
;         const int s = tid >> 2, cq = (tid & 3) * 32;
;         const size_t row = m0 + s;
;         const float mean = vs1[row] * (1.f / 1024.f); const float var = vs2[row] * (1.f / 1024.f) - mean * mean; const float rstd = rsqrtf(fmaxf(var, 0.f) + EPS);
; #pragma unroll
;         for (int j = 0; j < 4; ++j) {
;             const int cc = cq + 8 * j;
;             const v4u vr = *(const v4u*)(Vb + row * 1024 + c0 + cc);
;             const f32x4 w0 = *(const f32x4*)(lnw + c0 + cc), w1 = *(const f32x4*)(lnw + c0 + cc + 4), b0 = *(const f32x4*)(lnb + c0 + cc), b1 = *(const f32x4*)(lnb + c0 + cc + 4);
.LBB0_765:
	v_mov_b32_e32 v1, v145
	s_ashr_i32 s0, s7, 3
	v_readfirstlane_b32 s2, v1
	s_ashr_i32 s2, s2, 2
	s_ashr_i32 s1, s0, 31
	v_bfi_b32 v84, -16, s2, v1
	s_lshl_b64 s[0:1], s[0:1], 7
	v_ashrrev_i32_e32 v85, 31, v84
	v_lshl_add_u64 v[82:83], s[0:1], 0, v[84:85]
	v_ashrrev_i32_e32 v34, 2, v1
	v_lshlrev_b32_e32 v35, 5, v1
	v_bfe_u32 v88, v1, 4, 2
	v_and_b32_e32 v90, 0x60, v35
	v_readlane_b32 s36, v251, 5
	s_lshl_b64 s[2:3], s[26:27], 2
	v_readlane_b32 s42, v251, 11
	v_readlane_b32 s43, v251, 12
	v_readlane_b32 s44, v251, 13
	v_readlane_b32 s45, v251, 14
	v_lshlrev_b32_e32 v89, 2, v90
	v_readlane_b32 s48, v251, 17
	v_readlane_b32 s49, v251, 18
	v_readlane_b32 s50, v251, 19
	v_readlane_b32 s51, v251, 20
	v_readlane_b32 s50, v255, 24
	v_readlane_b32 s51, v255, 25
	v_readlane_b32 s37, v251, 6
	v_readlane_b32 s38, v251, 7
	v_readlane_b32 s39, v251, 8
	v_readlane_b32 s40, v251, 9
	v_readlane_b32 s41, v251, 10
	v_readlane_b32 s46, v251, 15
	v_readlane_b32 s47, v251, 16
	v_lshlrev_b32_e32 v235, 1, v34
	s_cmp_eq_u32 s101, 0
	s_cbranch_scc1 .Lg3_nf
	s_mov_b32 s100, s7
	s_ashr_i32 s4, s100, 3
	s_ashr_i32 s5, s4, 31
	s_lshl_b64 s[4:5], s[4:5], 7
	s_and_b32 s100, s100, 7
	s_lshl_b32 s100, s100, 7
	v_mov_b32_e32 v36, v84
	v_mov_b32_e32 v37, 0
	v_lshl_add_u64 v[36:37], s[4:5], 0, v[36:37]
	v_lshlrev_b64 v[36:37], 10, v[36:37]
	v_or_b32_e32 v36, s100, v36
	v_or_b32_e32 v37, s27, v37
	v_lshl_or_b32 v36, v88, 3, v36
	v_lshlrev_b64 v[36:37], 1, v[36:37]
	v_lshl_add_u64 v[38:39], s[34:35], 0, v[36:37]
	v_lshl_add_u64 v[40:41], s[50:51], 0, v[36:37]
	global_load_dwordx4 v[92:95], v[38:39], off nt
	global_load_dwordx4 v[96:99], v[38:39], off offset:64 nt
	global_load_dwordx4 v[100:103], v[38:39], off offset:128 nt
	global_load_dwordx4 v[104:107], v[38:39], off offset:192 nt
	global_load_dwordx4 v[108:111], v[40:41], off nt
	global_load_dwordx4 v[112:115], v[40:41], off offset:64 nt
	global_load_dwordx4 v[116:119], v[40:41], off offset:128 nt
	global_load_dwordx4 v[120:123], v[40:41], off offset:192 nt
	v_ashrrev_i32_e32 v42, 2, v145
	v_ashrrev_i32_e32 v43, 31, v42
	v_lshl_add_u64 v[42:43], s[4:5], 0, v[42:43]
	v_lshlrev_b64 v[44:45], 2, v[42:43]
	v_readlane_b32 s4, v251, 21
	v_readlane_b32 s5, v251, 22
	s_nop 1
	v_lshl_add_u64 v[46:47], s[4:5], 0, v[44:45]
	global_load_dword v244, v[46:47], off
	v_readlane_b32 s4, v251, 23
	v_readlane_b32 s5, v251, 24
	s_nop 1
	v_lshl_add_u64 v[46:47], s[4:5], 0, v[44:45]
	global_load_dword v245, v[46:47], off
	v_lshlrev_b64 v[42:43], 11, v[42:43]
	v_readlane_b32 s4, v253, 0
	v_readlane_b32 s5, v253, 1
	s_nop 1
	v_lshl_add_u64 v[42:43], s[4:5], 0, v[42:43]
	s_lshl_b32 s4, s100, 1
	s_mov_b32 s5, 0
	v_lshl_add_u64 v[42:43], v[42:43], 0, s[4:5]
	v_and_b32_e32 v48, 3, v145
	v_lshlrev_b32_e32 v48, 6, v48
	v_mov_b32_e32 v49, 0
	v_lshl_add_u64 v[42:43], v[42:43], 0, v[48:49]
	global_load_dwordx4 v[124:127], v[42:43], off offset:48 nt
	global_load_dwordx4 v[128:131], v[42:43], off offset:32 nt
	global_load_dwordx4 v[132:135], v[42:43], off offset:16 nt
	global_load_dwordx4 v[246:249], v[42:43], off nt
	s_mov_b32 s101, 0
.Lg3_nf:
	s_add_u32 s4, s42, s2
	s_addc_u32 s5, s43, s3
	s_add_u32 s2, s44, s2
	s_addc_u32 s3, s45, s3
	global_load_dwordx4 v[46:49], v89, s[4:5] offset:48
	global_load_dwordx4 v[58:61], v89, s[4:5] offset:32
	global_load_dwordx4 v[66:69], v89, s[4:5] offset:16
	global_load_dwordx4 v[74:77], v89, s[4:5]
	global_load_dwordx4 v[50:53], v89, s[2:3] offset:48
	global_load_dwordx4 v[62:65], v89, s[2:3] offset:32
	global_load_dwordx4 v[70:73], v89, s[2:3] offset:16
	global_load_dwordx4 v[78:81], v89, s[2:3]
	global_load_dwordx4 v[200:203], v89, s[4:5] offset:112
	global_load_dwordx4 v[204:207], v89, s[4:5] offset:96
	global_load_dwordx4 v[208:211], v89, s[4:5] offset:80
	global_load_dwordx4 v[224:227], v89, s[4:5] offset:64
	global_load_dwordx4 v[212:215], v89, s[2:3] offset:112
	global_load_dwordx4 v[216:219], v89, s[2:3] offset:96
	global_load_dwordx4 v[220:223], v89, s[2:3] offset:80
	global_load_dwordx4 v[228:231], v89, s[2:3] offset:64
	v_add_u32_e32 v198, s26, v84
	v_ashrrev_i32_e32 v199, 31, v198
	v_lshl_add_u64 v[198:199], v[198:199], 2, s[48:49]
	global_load_dword v232, v[198:199], off
	s_waitcnt vmcnt(17)
	v_mov_b32_e32 v30, v92
	v_mov_b32_e32 v31, v93
	v_mov_b32_e32 v32, v94
	v_mov_b32_e32 v33, v95
	v_mov_b32_e32 v22, v96
	v_mov_b32_e32 v23, v97
	v_mov_b32_e32 v24, v98
	v_mov_b32_e32 v25, v99
	v_mov_b32_e32 v14, v100
	v_mov_b32_e32 v15, v101
	v_mov_b32_e32 v16, v102
	v_mov_b32_e32 v17, v103
	v_mov_b32_e32 v6, v104
	v_mov_b32_e32 v7, v105
	v_mov_b32_e32 v8, v106
	v_mov_b32_e32 v9, v107
	v_mov_b32_e32 v26, v108
	v_mov_b32_e32 v27, v109
	v_mov_b32_e32 v28, v110
	v_mov_b32_e32 v29, v111
	v_mov_b32_e32 v18, v112
	v_mov_b32_e32 v19, v113
	v_mov_b32_e32 v20, v114
	v_mov_b32_e32 v21, v115
	v_mov_b32_e32 v10, v116
	v_mov_b32_e32 v11, v117
	v_mov_b32_e32 v12, v118
	v_mov_b32_e32 v13, v119
	v_mov_b32_e32 v2, v120
	v_mov_b32_e32 v3, v121
	v_mov_b32_e32 v4, v122
	v_mov_b32_e32 v5, v123
	v_mov_b32_e32 v34, v124
	v_mov_b32_e32 v35, v125
	v_mov_b32_e32 v36, v126
	v_mov_b32_e32 v37, v127
	v_mov_b32_e32 v38, v128
	v_mov_b32_e32 v39, v129
	v_mov_b32_e32 v40, v130
	v_mov_b32_e32 v41, v131
	v_mov_b32_e32 v42, v132
	v_mov_b32_e32 v43, v133
	v_mov_b32_e32 v44, v134
	v_mov_b32_e32 v45, v135
	v_mov_b32_e32 v54, v246
	v_mov_b32_e32 v55, v247
	v_mov_b32_e32 v56, v248
	v_mov_b32_e32 v57, v249
	v_mov_b32_e32 v197, v244
	v_mov_b32_e32 v196, v245
	v_mul_u32_u24_e32 v90, 0x110, v90
	s_add_i32 s7, s7, s84
	s_lshl_b64 s[0:1], s[26:27], 1
	s_waitcnt vmcnt(0)
; #define LAS __attribute__((address_space(3)))
; __device__ __forceinline__ float bflo(unsigned u) { return __uint_as_float(u << 16); }
; __device__ __forceinline__ float bfhi(unsigned u) { return __uint_as_float(u & 0xffff0000u); }
; __device__ __forceinline__ unsigned short f2bf(float f) { return (unsigned short)(pk2(f, 0.f) & 0xffffu); }
; __device__ __forceinline__ void gmlp_unit(LAS unsigned char* lds, int unit, const bf16* U, const bf16* Vb, bf16* Y, const float* vs1, const float* vs2,
;                                           const float* lnw, const float* lnb, const float* bs) {
;     ...
;         const float mean = vs1[row] * (1.f / 1024.f); const float var = vs2[row] * (1.f / 1024.f) - mean * mean; const float rstd = rsqrtf(fmaxf(var, 0.f) + EPS);
; #pragma unroll
;         for (int j = 0; j < 4; ++j) {
;             const int cc = cq + 8 * j;
;             const v4u vr = *(const v4u*)(Vb + row * 1024 + c0 + cc);
;             const f32x4 w0 = *(const f32x4*)(lnw + c0 + cc), w1 = *(const f32x4*)(lnw + c0 + cc + 4), b0 = *(const f32x4*)(lnb + c0 + cc), b1 = *(const f32x4*)(lnb + c0 + cc + 4);
;             LAS bf16* vd = Vt + cc * 136 + s;
;             vd[0 * 136] = f2bf((bflo(vr.x) - mean) * rstd * w0[0] + b0[0]); vd[1 * 136] = f2bf((bfhi(vr.x) - mean) * rstd * w0[1] + b0[1]);
;             vd[2 * 136] = f2bf((bflo(vr.y) - mean) * rstd * w0[2] + b0[2]); vd[3 * 136] = f2bf((bfhi(vr.y) - mean) * rstd * w0[3] + b0[3]);
;             vd[4 * 136] = f2bf((bflo(vr.z) - mean) * rstd * w1[0] + b1[0]); vd[5 * 136] = f2bf((bfhi(vr.z) - mean) * rstd * w1[1] + b1[1]);
;             vd[6 * 136] = f2bf((bflo(vr.w) - mean) * rstd * w1[2] + b1[2]); vd[7 * 136] = f2bf((bfhi(vr.w) - mean) * rstd * w1[3] + b1[3]);
;         }
	v_mul_f32_e32 v86, 0x3a800000, v196
	v_mul_f32_e32 v87, 0x3a800000, v197
	v_fma_f32 v233, -v87, v87, v86
	v_max_f32_e32 v233, 0, v233
	v_add_f32_e32 v233, 0x358637bd, v233
	v_rsq_f32_e32 v85, v233
	s_nop 0
	v_add3_u32 v86, 0, v235, v90
	v_lshlrev_b32_e32 v90, 16, v54
	v_and_b32_e32 v54, 0xffff0000, v54
	v_sub_f32_e32 v54, v54, v87
	v_mul_f32_e32 v54, v54, v85
	v_fma_f32 v54, v75, v54, v79
	v_cvt_pk_bf16_f32 v54, v54, s0
	ds_write_b16 v86, v54 offset:35088
	v_lshlrev_b32_e32 v54, 16, v55
	v_sub_f32_e32 v54, v54, v87
	v_mul_f32_e32 v54, v54, v85
	v_fma_f32 v54, v76, v54, v80
	v_cvt_pk_bf16_f32 v54, v54, s0
	ds_write_b16 v86, v54 offset:35360
	v_and_b32_e32 v54, 0xffff0000, v55
	v_sub_f32_e32 v54, v54, v87
	v_mul_f32_e32 v54, v54, v85
	v_fmac_f32_e32 v81, v77, v54
	v_cvt_pk_bf16_f32 v54, v81, s0
	ds_write_b16 v86, v54 offset:35632
	v_lshlrev_b32_e32 v54, 16, v56
	v_sub_f32_e32 v54, v54, v87
	v_mul_f32_e32 v54, v54, v85
	v_fma_f32 v54, v66, v54, v70
	v_cvt_pk_bf16_f32 v54, v54, s0
	ds_write_b16 v86, v54 offset:35904
	v_and_b32_e32 v54, 0xffff0000, v56
	v_sub_f32_e32 v54, v54, v87
	v_mul_f32_e32 v54, v54, v85
	v_fma_f32 v54, v67, v54, v71
	v_cvt_pk_bf16_f32 v54, v54, s0
	ds_write_b16 v86, v54 offset:36176
	v_lshlrev_b32_e32 v54, 16, v57
	v_sub_f32_e32 v54, v54, v87
	v_mul_f32_e32 v54, v54, v85
	v_fma_f32 v54, v68, v54, v72
	v_cvt_pk_bf16_f32 v54, v54, s0
	ds_write_b16 v86, v54 offset:36448
	v_and_b32_e32 v54, 0xffff0000, v57
	v_sub_f32_e32 v54, v54, v87
	v_mul_f32_e32 v54, v54, v85
	v_fmac_f32_e32 v73, v69, v54
	v_cvt_pk_bf16_f32 v54, v73, s0
	ds_write_b16 v86, v54 offset:36720
	v_lshlrev_b32_e32 v54, 16, v42
	v_and_b32_e32 v42, 0xffff0000, v42
	v_sub_f32_e32 v42, v42, v87
	v_mul_f32_e32 v42, v85, v42
	v_fma_f32 v42, v59, v42, v63
	v_cvt_pk_bf16_f32 v42, v42, s0
	ds_write_b16 v86, v42 offset:37264
	v_lshlrev_b32_e32 v42, 16, v43
	v_sub_f32_e32 v42, v42, v87
	v_mul_f32_e32 v42, v85, v42
	v_fma_f32 v42, v60, v42, v64
	v_cvt_pk_bf16_f32 v42, v42, s0
	ds_write_b16 v86, v42 offset:37536
	v_and_b32_e32 v42, 0xffff0000, v43
	v_sub_f32_e32 v42, v42, v87
	v_mul_f32_e32 v42, v85, v42
	v_fmac_f32_e32 v65, v61, v42
	v_cvt_pk_bf16_f32 v42, v65, s0
	ds_write_b16 v86, v42 offset:37808
	v_lshlrev_b32_e32 v42, 16, v44
	v_sub_f32_e32 v42, v42, v87
	v_mul_f32_e32 v42, v85, v42
	v_fma_f32 v42, v46, v42, v50
	v_cvt_pk_bf16_f32 v42, v42, s0
	ds_write_b16 v86, v42 offset:38080
	v_and_b32_e32 v42, 0xffff0000, v44
	v_sub_f32_e32 v42, v42, v87
	v_mul_f32_e32 v42, v85, v42
	v_fma_f32 v42, v47, v42, v51
	v_cvt_pk_bf16_f32 v42, v42, s0
	ds_write_b16 v86, v42 offset:38352
	v_lshlrev_b32_e32 v42, 16, v45
	v_sub_f32_e32 v42, v42, v87
	v_mul_f32_e32 v42, v85, v42
	v_fma_f32 v42, v48, v42, v52
	v_cvt_pk_bf16_f32 v42, v42, s0
	ds_write_b16 v86, v42 offset:38624
	v_and_b32_e32 v42, 0xffff0000, v45
	v_sub_f32_e32 v90, v90, v87
	v_sub_f32_e32 v54, v54, v87
	v_sub_f32_e32 v42, v42, v87
	v_mul_f32_e32 v90, v90, v85
	v_mul_f32_e32 v54, v85, v54
	v_mul_f32_e32 v42, v85, v42
	v_fma_f32 v74, v74, v90, v78
	v_fma_f32 v54, v58, v54, v62
	v_fmac_f32_e32 v53, v49, v42
	v_cvt_pk_bf16_f32 v74, v74, s0
	v_cvt_pk_bf16_f32 v54, v54, s0
	v_cvt_pk_bf16_f32 v42, v53, s0
	ds_write_b16 v86, v74 offset:34816
	ds_write_b16 v86, v54 offset:36992
	ds_write_b16 v86, v42 offset:38896
	v_lshlrev_b32_e32 v74, 16, v38
	v_and_b32_e32 v38, 0xffff0000, v38
	v_sub_f32_e32 v38, v38, v87
	v_mul_f32_e32 v38, v85, v38
	v_sub_f32_e32 v74, v74, v87
	v_mul_f32_e32 v74, v85, v74
	s_movk_i32 s2, 0x110
	v_fma_f32 v38, v225, v38, v229
	v_cvt_pk_bf16_f32 v38, v38, s0
	ds_write_b16 v86, v38 offset:39440
	v_lshlrev_b32_e32 v38, 16, v39
	v_sub_f32_e32 v38, v38, v87
	v_mul_f32_e32 v38, v85, v38
	v_fma_f32 v38, v226, v38, v230
	v_cvt_pk_bf16_f32 v38, v38, s0
	ds_write_b16 v86, v38 offset:39712
	v_and_b32_e32 v38, 0xffff0000, v39
	v_sub_f32_e32 v38, v38, v87
	v_mul_f32_e32 v38, v85, v38
	v_fmac_f32_e32 v231, v227, v38
	v_cvt_pk_bf16_f32 v38, v231, s0
	ds_write_b16 v86, v38 offset:39984
	v_lshlrev_b32_e32 v38, 16, v40
	v_sub_f32_e32 v38, v38, v87
	v_mul_f32_e32 v38, v85, v38
	v_fma_f32 v38, v208, v38, v220
	v_cvt_pk_bf16_f32 v38, v38, s0
	ds_write_b16 v86, v38 offset:40256
	v_and_b32_e32 v38, 0xffff0000, v40
	v_sub_f32_e32 v38, v38, v87
	v_mul_f32_e32 v38, v85, v38
	v_fma_f32 v38, v209, v38, v221
	v_cvt_pk_bf16_f32 v38, v38, s0
	ds_write_b16 v86, v38 offset:40528
	v_lshlrev_b32_e32 v38, 16, v41
	v_sub_f32_e32 v38, v38, v87
	v_mul_f32_e32 v38, v85, v38
	v_fma_f32 v38, v210, v38, v222
	v_cvt_pk_bf16_f32 v38, v38, s0
	ds_write_b16 v86, v38 offset:40800
	v_and_b32_e32 v38, 0xffff0000, v41
	v_sub_f32_e32 v38, v38, v87
	v_mul_f32_e32 v38, v85, v38
	v_fmac_f32_e32 v223, v211, v38
	v_cvt_pk_bf16_f32 v38, v223, s0
	ds_write_b16 v86, v38 offset:41072
	v_lshlrev_b32_e32 v38, 16, v34
	v_and_b32_e32 v34, 0xffff0000, v34
	v_sub_f32_e32 v34, v34, v87
	v_mul_f32_e32 v34, v85, v34
	v_fma_f32 v34, v205, v34, v217
	v_cvt_pk_bf16_f32 v34, v34, s0
	ds_write_b16 v86, v34 offset:41616
	v_lshlrev_b32_e32 v34, 16, v35
	v_sub_f32_e32 v34, v34, v87
	v_mul_f32_e32 v34, v85, v34
	v_fma_f32 v34, v206, v34, v218
	v_cvt_pk_bf16_f32 v34, v34, s0
	ds_write_b16 v86, v34 offset:41888
	v_and_b32_e32 v34, 0xffff0000, v35
	v_sub_f32_e32 v34, v34, v87
	v_mul_f32_e32 v34, v85, v34
	v_fmac_f32_e32 v219, v207, v34
	v_cvt_pk_bf16_f32 v34, v219, s0
	ds_write_b16 v86, v34 offset:42160
	v_lshlrev_b32_e32 v34, 16, v36
	v_sub_f32_e32 v34, v34, v87
	v_mul_f32_e32 v34, v85, v34
	v_fma_f32 v34, v200, v34, v212
	v_cvt_pk_bf16_f32 v34, v34, s0
	ds_write_b16 v86, v34 offset:42432
	v_and_b32_e32 v34, 0xffff0000, v36
	v_sub_f32_e32 v34, v34, v87
	v_mul_f32_e32 v34, v85, v34
; #define LAS __attribute__((address_space(3)))
; __device__ __forceinline__ float bflo(unsigned u) { return __uint_as_float(u << 16); }
; __device__ __forceinline__ float bfhi(unsigned u) { return __uint_as_float(u & 0xffff0000u); }
; __device__ __forceinline__ void gmlp_unit(LAS unsigned char* lds, int unit, const bf16* U, const bf16* Vb, bf16* Y, const float* vs1, const float* vs2,
;                                           const float* lnw, const float* lnb, const float* bs) {
;     ...
;             vd[0 * 136] = f2bf((bflo(vr.x) - mean) * rstd * w0[0] + b0[0]); vd[1 * 136] = f2bf((bfhi(vr.x) - mean) * rstd * w0[1] + b0[1]);
;             vd[2 * 136] = f2bf((bflo(vr.y) - mean) * rstd * w0[2] + b0[2]); vd[3 * 136] = f2bf((bfhi(vr.y) - mean) * rstd * w0[3] + b0[3]);
;             vd[4 * 136] = f2bf((bflo(vr.z) - mean) * rstd * w1[0] + b1[0]); vd[5 * 136] = f2bf((bfhi(vr.z) - mean) * rstd * w1[1] + b1[1]);
;             vd[6 * 136] = f2bf((bflo(vr.w) - mean) * rstd * w1[2] + b1[2]); vd[7 * 136] = f2bf((bfhi(vr.w) - mean) * rstd * w1[3] + b1[3]);
;         }
;     }
;     LBAR();
;     bf16x8 bw[4];
; #pragma unroll
;     for (int ks = 0; ks < 4; ++ks) bw[ks] = *(const LAS bf16x8*)(Wa + (16 * w + l16) * 136 + 32 * ks + 8 * g4);
;     const float bias = bs[g * 128 + t];
; #pragma unroll
;     for (int j = 0; j < 4; ++j) {
;         const int crow = 32 * j + 8 * (l16 >> 2) + (l16 & 3);
;         f32x4 e4 = (f32x4){0.f, 0.f, 0.f, 0.f}, o4 = e4;
; #pragma unroll
;         for (int ks = 0; ks < 4; ++ks) {
;             const bf16x8 ae = *(const LAS bf16x8*)(Vt + crow * 136 + 32 * ks + 8 * g4), ao = *(const LAS bf16x8*)(Vt + (crow + 4) * 136 + 32 * ks + 8 * g4);
;             e4 = mfma16(ae, bw[ks], e4); o4 = mfma16(ao, bw[ks], o4);
;         }
;         const size_t off = (m0 + t) * 1024 + c0 + 32 * j + 8 * g4;
;         const v4u u4 = uu[j], g4v = gg[j];
;         v4u y;
;         y.x = pk2(bflo(u4.x) * (e4[0] + bias) * bflo(g4v.x), bfhi(u4.x) * (e4[1] + bias) * bfhi(g4v.x)); y.y = pk2(bflo(u4.y) * (e4[2] + bias) * bflo(g4v.y), bfhi(u4.y) * (e4[3] + bias) * bfhi(g4v.y));
;         y.z = pk2(bflo(u4.z) * (o4[0] + bias) * bflo(g4v.z), bfhi(u4.z) * (o4[1] + bias) * bfhi(g4v.z)); y.w = pk2(bflo(u4.w) * (o4[2] + bias) * bflo(g4v.w), bfhi(u4.w) * (o4[3] + bias) * bfhi(g4v.w));
;         *(v4u*)(Y + off) = y;
	v_fma_f32 v34, v201, v34, v213
	v_cvt_pk_bf16_f32 v34, v34, s0
	ds_write_b16 v86, v34 offset:42704
	v_lshlrev_b32_e32 v34, 16, v37
	v_sub_f32_e32 v34, v34, v87
	v_mul_f32_e32 v34, v85, v34
	v_fma_f32 v34, v202, v34, v214
	v_cvt_pk_bf16_f32 v34, v34, s0
	ds_write_b16 v86, v34 offset:42976
	v_and_b32_e32 v34, 0xffff0000, v37
	v_sub_f32_e32 v38, v38, v87
	v_sub_f32_e32 v34, v34, v87
	v_mul_f32_e32 v38, v85, v38
	v_mul_f32_e32 v34, v85, v34
	v_fma_f32 v224, v224, v74, v228
	v_fma_f32 v38, v204, v38, v216
	v_fmac_f32_e32 v215, v203, v34
	v_cvt_pk_bf16_f32 v224, v224, s0
	v_cvt_pk_bf16_f32 v38, v38, s0
	v_cvt_pk_bf16_f32 v34, v215, s0
	v_add_u32_e32 v50, s26, v84
	ds_write_b16 v86, v224 offset:39168
	ds_write_b16 v86, v38 offset:41344
	ds_write_b16 v86, v34 offset:43248
	s_sub_i32 s100, s7, s84
	s_cmpk_lt_i32 s7, 0x400
	s_cselect_b32 s100, s7, s100
	s_ashr_i32 s4, s100, 3
	s_ashr_i32 s5, s4, 31
	s_lshl_b64 s[4:5], s[4:5], 7
	s_and_b32 s100, s100, 7
	s_lshl_b32 s100, s100, 7
	v_mov_b32_e32 v36, v84
	v_mov_b32_e32 v37, 0
	v_lshl_add_u64 v[36:37], s[4:5], 0, v[36:37]
	v_lshlrev_b64 v[36:37], 10, v[36:37]
	v_or_b32_e32 v36, s100, v36
	v_or_b32_e32 v37, s27, v37
	v_lshl_or_b32 v36, v88, 3, v36
	v_lshlrev_b64 v[36:37], 1, v[36:37]
	v_lshl_add_u64 v[38:39], s[34:35], 0, v[36:37]
	v_lshl_add_u64 v[40:41], s[50:51], 0, v[36:37]
	global_load_dwordx4 v[92:95], v[38:39], off nt
	global_load_dwordx4 v[96:99], v[38:39], off offset:64 nt
	global_load_dwordx4 v[100:103], v[38:39], off offset:128 nt
	global_load_dwordx4 v[104:107], v[38:39], off offset:192 nt
	global_load_dwordx4 v[108:111], v[40:41], off nt
	global_load_dwordx4 v[112:115], v[40:41], off offset:64 nt
	global_load_dwordx4 v[116:119], v[40:41], off offset:128 nt
	global_load_dwordx4 v[120:123], v[40:41], off offset:192 nt
	v_ashrrev_i32_e32 v42, 2, v145
	v_ashrrev_i32_e32 v43, 31, v42
	v_lshl_add_u64 v[42:43], s[4:5], 0, v[42:43]
	v_lshlrev_b64 v[44:45], 2, v[42:43]
	v_readlane_b32 s4, v251, 21
	v_readlane_b32 s5, v251, 22
	s_nop 1
	v_lshl_add_u64 v[46:47], s[4:5], 0, v[44:45]
	global_load_dword v244, v[46:47], off
	v_readlane_b32 s4, v251, 23
	v_readlane_b32 s5, v251, 24
	s_nop 1
	v_lshl_add_u64 v[46:47], s[4:5], 0, v[44:45]
	global_load_dword v245, v[46:47], off
	v_lshlrev_b64 v[42:43], 11, v[42:43]
	v_readlane_b32 s4, v253, 0
	v_readlane_b32 s5, v253, 1
	s_nop 1
	v_lshl_add_u64 v[42:43], s[4:5], 0, v[42:43]
	s_lshl_b32 s4, s100, 1
	s_mov_b32 s5, 0
	v_lshl_add_u64 v[42:43], v[42:43], 0, s[4:5]
	v_and_b32_e32 v48, 3, v145
	v_lshlrev_b32_e32 v48, 6, v48
	v_mov_b32_e32 v49, 0
	v_lshl_add_u64 v[42:43], v[42:43], 0, v[48:49]
	global_load_dwordx4 v[124:127], v[42:43], off offset:48 nt
	global_load_dwordx4 v[128:131], v[42:43], off offset:32 nt
	global_load_dwordx4 v[132:135], v[42:43], off offset:16 nt
	global_load_dwordx4 v[246:249], v[42:43], off nt
	v_mul_lo_u32 v34, v84, s2
	v_lshlrev_b32_e32 v54, 4, v88
	v_ashrrev_i32_e32 v51, 31, v50
	s_waitcnt lgkmcnt(0)
	s_barrier
	v_add3_u32 v34, 0, v34, v54
	v_lshl_add_u64 v[50:51], v[50:51], 2, s[48:49]
	ds_read_b128 v[46:49], v34
	ds_read_b128 v[42:45], v34 offset:64
	ds_read_b128 v[38:41], v34 offset:128
	ds_read_b128 v[34:37], v34 offset:192
	v_mov_b32_e32 v50, v232
	v_lshlrev_b32_e32 v51, 1, v1
	v_and_b32_e32 v1, 3, v1
	v_and_or_b32 v1, v51, 24, v1
	v_lshlrev_b64 v[52:53], 11, v[82:83]
	v_lshl_add_u64 v[52:53], s[50:51], 0, v[52:53]
	v_mul_u32_u24_e32 v1, 0x110, v1
	v_lshl_add_u64 v[52:53], v[52:53], 0, s[0:1]
	v_mov_b32_e32 v55, v0
	v_add3_u32 v1, 0, v1, v54
	v_lshl_add_u64 v[52:53], v[52:53], 0, v[54:55]
	ds_read_b128 v[54:57], v1 offset:34816
	ds_read_b128 v[58:61], v1 offset:35904
	ds_read_b128 v[62:65], v1 offset:34880
	ds_read_b128 v[66:69], v1 offset:35968
	s_waitcnt lgkmcnt(3)
	v_mfma_f32_16x16x32_bf16 v[54:57], v[54:57], v[46:49], 0
	v_readlane_b32 s0, v254, 54
	s_add_i32 s6, s6, s0
	s_cmpk_gt_i32 s7, 0x3ff
	s_waitcnt lgkmcnt(2)
	v_mfma_f32_16x16x32_bf16 v[58:61], v[58:61], v[46:49], 0
	s_waitcnt lgkmcnt(1)
	v_mfma_f32_16x16x32_bf16 v[54:57], v[62:65], v[42:45], v[54:57]
	s_waitcnt lgkmcnt(0)
	v_mfma_f32_16x16x32_bf16 v[58:61], v[66:69], v[42:45], v[58:61]
	ds_read_b128 v[62:65], v1 offset:34944
	ds_read_b128 v[66:69], v1 offset:36032
	s_waitcnt lgkmcnt(1)
	v_mfma_f32_16x16x32_bf16 v[54:57], v[62:65], v[38:41], v[54:57]
	s_waitcnt lgkmcnt(0)
	v_mfma_f32_16x16x32_bf16 v[58:61], v[66:69], v[38:41], v[58:61]
	ds_read_b128 v[62:65], v1 offset:35008
	ds_read_b128 v[66:69], v1 offset:36096
	s_waitcnt lgkmcnt(1)
	v_mfma_f32_16x16x32_bf16 v[54:57], v[62:65], v[34:37], v[54:57]
	v_lshlrev_b32_e32 v62, 16, v30
	v_and_b32_e32 v63, 0xffff0000, v30
	v_lshlrev_b32_e32 v30, 16, v31
	s_waitcnt lgkmcnt(0)
	v_mfma_f32_16x16x32_bf16 v[58:61], v[66:69], v[34:37], v[58:61]
	v_and_b32_e32 v31, 0xffff0000, v31
	s_nop 0
	v_pk_add_f32 v[54:55], v[50:51], v[54:55] op_sel_hi:[0,1]
	v_pk_mul_f32 v[54:55], v[54:55], v[62:63]
	v_lshlrev_b32_e32 v62, 16, v26
	v_and_b32_e32 v63, 0xffff0000, v26
	v_pk_mul_f32 v[54:55], v[54:55], v[62:63]
	s_nop 0
	v_cvt_pk_bf16_f32 v26, v54, v55
	v_pk_add_f32 v[54:55], v[50:51], v[56:57] op_sel_hi:[0,1]
	v_pk_mul_f32 v[30:31], v[54:55], v[30:31]
	v_lshlrev_b32_e32 v54, 16, v27
	v_and_b32_e32 v55, 0xffff0000, v27
	v_pk_mul_f32 v[30:31], v[30:31], v[54:55]
	v_pk_add_f32 v[54:55], v[50:51], v[58:59] op_sel_hi:[0,1]
	v_cvt_pk_bf16_f32 v27, v30, v31
	v_lshlrev_b32_e32 v30, 16, v32
	v_and_b32_e32 v31, 0xffff0000, v32
	v_pk_mul_f32 v[30:31], v[54:55], v[30:31]
	v_lshlrev_b32_e32 v54, 16, v28
	v_and_b32_e32 v55, 0xffff0000, v28
	v_pk_mul_f32 v[30:31], v[30:31], v[54:55]
	s_nop 0
	v_cvt_pk_bf16_f32 v28, v30, v31
	v_lshlrev_b32_e32 v30, 16, v33
	v_and_b32_e32 v31, 0xffff0000, v33
	v_pk_add_f32 v[32:33], v[50:51], v[60:61] op_sel_hi:[0,1]
	v_pk_mul_f32 v[30:31], v[32:33], v[30:31]
	v_lshlrev_b32_e32 v32, 16, v29
	v_and_b32_e32 v33, 0xffff0000, v29
	v_pk_mul_f32 v[30:31], v[30:31], v[32:33]
	s_nop 0
	v_cvt_pk_bf16_f32 v29, v30, v31
	global_store_dwordx4 v[52:53], v[26:29], off
	ds_read_b128 v[26:29], v1 offset:43520
	ds_read_b128 v[30:33], v1 offset:44608
	ds_read_b128 v[54:57], v1 offset:43584
	ds_read_b128 v[58:61], v1 offset:44672
	s_waitcnt lgkmcnt(3)
; #define LAS __attribute__((address_space(3)))
; __device__ __forceinline__ float bflo(unsigned u) { return __uint_as_float(u << 16); }
; __device__ __forceinline__ float bfhi(unsigned u) { return __uint_as_float(u & 0xffff0000u); }
; __device__ __forceinline__ unsigned pk2(float lo, float hi) { f32x2_t v = {lo, hi}; bf16x2_t b = __builtin_convertvector(v, bf16x2_t); return __builtin_bit_cast(unsigned, b); }
; __device__ __forceinline__ f32x4 mfma16(bf16x8 a, bf16x8 b, f32x4 c) { return __builtin_amdgcn_mfma_f32_16x16x32_bf16(a, b, c, 0, 0, 0); }
; #define LBAR() do { asm volatile("s_waitcnt lgkmcnt(0)" ::: "memory"); __builtin_amdgcn_s_barrier(); asm volatile("" ::: "memory"); } while (0)
; __device__ __forceinline__ void gmlp_unit(LAS unsigned char* lds, int unit, const bf16* U, const bf16* Vb, bf16* Y, const float* vs1, const float* vs2,
;                                           const float* lnw, const float* lnb, const float* bs) {
;     ...
;     for (int j = 0; j < 4; ++j) {
;         const int crow = 32 * j + 8 * (l16 >> 2) + (l16 & 3);
;         f32x4 e4 = (f32x4){0.f, 0.f, 0.f, 0.f}, o4 = e4;
; #pragma unroll
;         for (int ks = 0; ks < 4; ++ks) {
;             const bf16x8 ae = *(const LAS bf16x8*)(Vt + crow * 136 + 32 * ks + 8 * g4), ao = *(const LAS bf16x8*)(Vt + (crow + 4) * 136 + 32 * ks + 8 * g4);
;             e4 = mfma16(ae, bw[ks], e4); o4 = mfma16(ao, bw[ks], o4);
;         }
;         const size_t off = (m0 + t) * 1024 + c0 + 32 * j + 8 * g4;
;         const v4u u4 = uu[j], g4v = gg[j];
;         v4u y;
;         y.x = pk2(bflo(u4.x) * (e4[0] + bias) * bflo(g4v.x), bfhi(u4.x) * (e4[1] + bias) * bfhi(g4v.x)); y.y = pk2(bflo(u4.y) * (e4[2] + bias) * bflo(g4v.y), bfhi(u4.y) * (e4[3] + bias) * bfhi(g4v.y));
;         y.z = pk2(bflo(u4.z) * (o4[0] + bias) * bflo(g4v.z), bfhi(u4.z) * (o4[1] + bias) * bfhi(g4v.z)); y.w = pk2(bflo(u4.w) * (o4[2] + bias) * bflo(g4v.w), bfhi(u4.w) * (o4[3] + bias) * bfhi(g4v.w));
;         *(v4u*)(Y + off) = y;
;     }
;     LBAR();
	v_mfma_f32_16x16x32_bf16 v[26:29], v[26:29], v[46:49], 0
	s_waitcnt lgkmcnt(2)
	v_mfma_f32_16x16x32_bf16 v[30:33], v[30:33], v[46:49], 0
	s_waitcnt lgkmcnt(1)
	v_mfma_f32_16x16x32_bf16 v[26:29], v[54:57], v[42:45], v[26:29]
	s_waitcnt lgkmcnt(0)
	v_mfma_f32_16x16x32_bf16 v[30:33], v[58:61], v[42:45], v[30:33]
	ds_read_b128 v[54:57], v1 offset:43648
	ds_read_b128 v[58:61], v1 offset:44736
	s_waitcnt lgkmcnt(1)
	v_mfma_f32_16x16x32_bf16 v[26:29], v[54:57], v[38:41], v[26:29]
	s_waitcnt lgkmcnt(0)
	v_mfma_f32_16x16x32_bf16 v[30:33], v[58:61], v[38:41], v[30:33]
	ds_read_b128 v[54:57], v1 offset:43712
	ds_read_b128 v[58:61], v1 offset:44800
	s_waitcnt lgkmcnt(1)
	v_mfma_f32_16x16x32_bf16 v[26:29], v[54:57], v[34:37], v[26:29]
	v_lshlrev_b32_e32 v54, 16, v22
	v_and_b32_e32 v55, 0xffff0000, v22
	v_lshlrev_b32_e32 v22, 16, v23
	s_waitcnt lgkmcnt(0)
	v_mfma_f32_16x16x32_bf16 v[30:33], v[58:61], v[34:37], v[30:33]
	s_nop 2
	v_add_f32_e64 v26, v50, v26
	v_add_f32_e64 v27, v50, v27
	v_pk_mul_f32 v[26:27], v[26:27], v[54:55]
	v_lshlrev_b32_e32 v54, 16, v18
	v_and_b32_e32 v55, 0xffff0000, v18
	v_pk_mul_f32 v[26:27], v[26:27], v[54:55]
	v_and_b32_e32 v23, 0xffff0000, v23
	v_cvt_pk_bf16_f32 v18, v26, v27
	v_pk_add_f32 v[26:27], v[50:51], v[28:29] op_sel_hi:[0,1]
	v_pk_mul_f32 v[22:23], v[26:27], v[22:23]
	v_lshlrev_b32_e32 v26, 16, v19
	v_and_b32_e32 v27, 0xffff0000, v19
	v_pk_mul_f32 v[22:23], v[22:23], v[26:27]
	v_pk_add_f32 v[26:27], v[50:51], v[30:31] op_sel_hi:[0,1]
	v_cvt_pk_bf16_f32 v19, v22, v23
	v_lshlrev_b32_e32 v22, 16, v24
	v_and_b32_e32 v23, 0xffff0000, v24
	v_pk_mul_f32 v[22:23], v[26:27], v[22:23]
	v_lshlrev_b32_e32 v26, 16, v20
	v_and_b32_e32 v27, 0xffff0000, v20
	v_pk_mul_f32 v[22:23], v[22:23], v[26:27]
	s_nop 0
	v_cvt_pk_bf16_f32 v20, v22, v23
	v_lshlrev_b32_e32 v22, 16, v25
	v_and_b32_e32 v23, 0xffff0000, v25
	v_pk_add_f32 v[24:25], v[50:51], v[32:33] op_sel_hi:[0,1]
	v_pk_mul_f32 v[22:23], v[24:25], v[22:23]
	v_lshlrev_b32_e32 v24, 16, v21
	v_and_b32_e32 v25, 0xffff0000, v21
	v_pk_mul_f32 v[22:23], v[22:23], v[24:25]
	s_nop 0
	v_cvt_pk_bf16_f32 v21, v22, v23
	global_store_dwordx4 v[52:53], v[18:21], off offset:64
	ds_read_b128 v[18:21], v1 offset:52224
	ds_read_b128 v[22:25], v1 offset:53312
	ds_read_b128 v[26:29], v1 offset:52288
	ds_read_b128 v[30:33], v1 offset:53376
	s_waitcnt lgkmcnt(3)
	v_mfma_f32_16x16x32_bf16 v[18:21], v[18:21], v[46:49], 0
	s_waitcnt lgkmcnt(2)
	v_mfma_f32_16x16x32_bf16 v[22:25], v[22:25], v[46:49], 0
	s_waitcnt lgkmcnt(1)
	v_mfma_f32_16x16x32_bf16 v[18:21], v[26:29], v[42:45], v[18:21]
	s_waitcnt lgkmcnt(0)
	v_mfma_f32_16x16x32_bf16 v[22:25], v[30:33], v[42:45], v[22:25]
	ds_read_b128 v[26:29], v1 offset:52352
	ds_read_b128 v[30:33], v1 offset:53440
	s_waitcnt lgkmcnt(1)
	v_mfma_f32_16x16x32_bf16 v[18:21], v[26:29], v[38:41], v[18:21]
	s_waitcnt lgkmcnt(0)
	v_mfma_f32_16x16x32_bf16 v[22:25], v[30:33], v[38:41], v[22:25]
	ds_read_b128 v[26:29], v1 offset:52416
	ds_read_b128 v[30:33], v1 offset:53504
	s_waitcnt lgkmcnt(1)
	v_mfma_f32_16x16x32_bf16 v[18:21], v[26:29], v[34:37], v[18:21]
	v_lshlrev_b32_e32 v26, 16, v14
	v_and_b32_e32 v27, 0xffff0000, v14
	v_lshlrev_b32_e32 v14, 16, v15
	s_waitcnt lgkmcnt(0)
	v_mfma_f32_16x16x32_bf16 v[22:25], v[30:33], v[34:37], v[22:25]
	s_nop 2
	v_add_f32_e64 v18, v50, v18
	v_add_f32_e64 v19, v50, v19
	v_pk_mul_f32 v[18:19], v[18:19], v[26:27]
	v_lshlrev_b32_e32 v26, 16, v10
	v_and_b32_e32 v27, 0xffff0000, v10
	v_pk_mul_f32 v[18:19], v[18:19], v[26:27]
	v_and_b32_e32 v15, 0xffff0000, v15
	v_cvt_pk_bf16_f32 v10, v18, v19
	v_pk_add_f32 v[18:19], v[50:51], v[20:21] op_sel_hi:[0,1]
	v_pk_mul_f32 v[14:15], v[18:19], v[14:15]
	v_lshlrev_b32_e32 v18, 16, v11
	v_and_b32_e32 v19, 0xffff0000, v11
	v_pk_mul_f32 v[14:15], v[14:15], v[18:19]
	v_pk_add_f32 v[18:19], v[50:51], v[22:23] op_sel_hi:[0,1]
	v_cvt_pk_bf16_f32 v11, v14, v15
	v_lshlrev_b32_e32 v14, 16, v16
	v_and_b32_e32 v15, 0xffff0000, v16
	v_pk_mul_f32 v[14:15], v[18:19], v[14:15]
	v_lshlrev_b32_e32 v18, 16, v12
	v_and_b32_e32 v19, 0xffff0000, v12
	v_pk_mul_f32 v[14:15], v[14:15], v[18:19]
	s_nop 0
	v_cvt_pk_bf16_f32 v12, v14, v15
	v_lshlrev_b32_e32 v14, 16, v17
	v_and_b32_e32 v15, 0xffff0000, v17
	v_pk_add_f32 v[16:17], v[50:51], v[24:25] op_sel_hi:[0,1]
	v_pk_mul_f32 v[14:15], v[16:17], v[14:15]
	v_lshlrev_b32_e32 v16, 16, v13
	v_and_b32_e32 v17, 0xffff0000, v13
	v_pk_mul_f32 v[14:15], v[14:15], v[16:17]
	s_nop 0
	v_cvt_pk_bf16_f32 v13, v14, v15
	global_store_dwordx4 v[52:53], v[10:13], off offset:128
	ds_read_b128 v[10:13], v1 offset:60928
	ds_read_b128 v[14:17], v1 offset:62016
	ds_read_b128 v[18:21], v1 offset:60992
	ds_read_b128 v[22:25], v1 offset:62080
	s_waitcnt lgkmcnt(3)
	v_mfma_f32_16x16x32_bf16 v[10:13], v[10:13], v[46:49], 0
	s_waitcnt lgkmcnt(2)
	v_mfma_f32_16x16x32_bf16 v[14:17], v[14:17], v[46:49], 0
	s_waitcnt lgkmcnt(1)
	v_mfma_f32_16x16x32_bf16 v[10:13], v[18:21], v[42:45], v[10:13]
	s_waitcnt lgkmcnt(0)
	v_mfma_f32_16x16x32_bf16 v[14:17], v[22:25], v[42:45], v[14:17]
	ds_read_b128 v[18:21], v1 offset:61056
	ds_read_b128 v[22:25], v1 offset:62144
	s_waitcnt lgkmcnt(1)
	v_mfma_f32_16x16x32_bf16 v[10:13], v[18:21], v[38:41], v[10:13]
	s_waitcnt lgkmcnt(0)
	v_mfma_f32_16x16x32_bf16 v[14:17], v[22:25], v[38:41], v[14:17]
	ds_read_b128 v[18:21], v1 offset:61120
	ds_read_b128 v[22:25], v1 offset:62208
	s_waitcnt lgkmcnt(1)
	v_mfma_f32_16x16x32_bf16 v[10:13], v[18:21], v[34:37], v[10:13]
	v_lshlrev_b32_e32 v18, 16, v6
	v_and_b32_e32 v19, 0xffff0000, v6
	v_lshlrev_b32_e32 v6, 16, v7
	s_waitcnt lgkmcnt(0)
	v_mfma_f32_16x16x32_bf16 v[14:17], v[22:25], v[34:37], v[14:17]
	s_nop 2
	v_add_f32_e64 v10, v50, v10
	v_add_f32_e64 v11, v50, v11
	v_pk_mul_f32 v[10:11], v[10:11], v[18:19]
	v_lshlrev_b32_e32 v18, 16, v2
	v_and_b32_e32 v19, 0xffff0000, v2
	v_pk_mul_f32 v[10:11], v[10:11], v[18:19]
	v_and_b32_e32 v7, 0xffff0000, v7
	v_cvt_pk_bf16_f32 v2, v10, v11
	v_pk_add_f32 v[10:11], v[50:51], v[12:13] op_sel_hi:[0,1]
	v_pk_mul_f32 v[6:7], v[10:11], v[6:7]
	v_lshlrev_b32_e32 v10, 16, v3
	v_and_b32_e32 v11, 0xffff0000, v3
	v_pk_mul_f32 v[6:7], v[6:7], v[10:11]
	v_pk_add_f32 v[10:11], v[50:51], v[14:15] op_sel_hi:[0,1]
	v_cvt_pk_bf16_f32 v3, v6, v7
	v_lshlrev_b32_e32 v6, 16, v8
	v_and_b32_e32 v7, 0xffff0000, v8
	v_pk_mul_f32 v[6:7], v[10:11], v[6:7]
	v_lshlrev_b32_e32 v10, 16, v4
	v_and_b32_e32 v11, 0xffff0000, v4
	v_pk_mul_f32 v[6:7], v[6:7], v[10:11]
	s_nop 0
	v_cvt_pk_bf16_f32 v4, v6, v7
	v_lshlrev_b32_e32 v6, 16, v9
	v_and_b32_e32 v7, 0xffff0000, v9
	v_pk_add_f32 v[8:9], v[50:51], v[16:17] op_sel_hi:[0,1]
	v_pk_mul_f32 v[6:7], v[8:9], v[6:7]
	v_lshlrev_b32_e32 v8, 16, v5
	v_and_b32_e32 v9, 0xffff0000, v5
	v_pk_mul_f32 v[6:7], v[6:7], v[8:9]
	s_nop 0
	v_cvt_pk_bf16_f32 v5, v6, v7
	global_store_dwordx4 v[52:53], v[2:5], off offset:192
	s_waitcnt lgkmcnt(0)
	s_barrier
	s_cbranch_scc1 .LBB0_762

; __device__ __forceinline__ float bflo(unsigned u) { return __uint_as_float(u << 16); }
; __device__ __forceinline__ float bfhi(unsigned u) { return __uint_as_float(u & 0xffff0000u); }
;     __device__ __forceinline__ void operator()(const f32x4 (&acc)[2][2][4][2], const pg8::Unit& u, int wr, int wc, int fr, int fq) const {
;         const int row0 = u.pm * 256 + wr * 64 + fr; const int c0 = u.pn * 256 + wc * 32 + 8 * fq;
; #pragma unroll
;         for (int ai = 0; ai < 2; ++ai)
; #pragma unroll
;             for (int m = 0; m < 4; ++m) {
;                 const int row = row0 + ai * 128 + m * 16; float s2 = 0.f;
; #pragma unroll
;                 for (int bj = 0; bj < 2; ++bj) {
;                     const size_t off = (size_t)row * 1024 + c0 + bj * 128;
;                     f32x4 x0, x1;
;                     if (xin) { x0 = *(const f32x4*)(xin + off); x1 = *(const f32x4*)(xin + off + 4); }
;                     else { const v4u xv = *(const v4u*)(xb + off); x0 = (f32x4){bflo(xv.x), bfhi(xv.x), bflo(xv.y), bfhi(xv.y)}; x1 = (f32x4){bflo(xv.z), bfhi(xv.z), bflo(xv.w), bfhi(xv.w)}; }
.LBB0_1380:
	v_lshl_add_u32 v176, s11, 8, v1
	v_lshl_or_b32 v174, s10, 8, v186
	v_ashrrev_i32_e32 v177, 31, v176
	v_ashrrev_i32_e32 v175, 31, v174
	v_lshlrev_b64 v[130:131], 10, v[176:177]
	v_lshl_add_u64 v[178:179], v[130:131], 0, v[174:175]
	v_cndmask_b32_e64 v130, 0, 1, s[28:29]
	v_readlane_b32 s54, v255, 22
	v_readlane_b32 s50, v255, 24
	v_cmp_ne_u32_e64 s[8:9], 1, v130
	s_andn2_b64 vcc, exec, s[28:29]
	v_lshl_add_u64 v[180:181], v[178:179], 2, s[14:15]
	v_readlane_b32 s55, v255, 23
	v_readlane_b32 s51, v255, 25
	s_cbranch_vccnz .LBB0_1382
	global_load_dwordx4 v[130:133], v[180:181], off offset:16 nt
	global_load_dwordx4 v[134:137], v[180:181], off nt
	s_mov_b64 s[2:3], 0
	s_branch .LBB0_1383

; __device__ __forceinline__ float bflo(unsigned u) { return __uint_as_float(u << 16); }
; __device__ __forceinline__ float bfhi(unsigned u) { return __uint_as_float(u & 0xffff0000u); }
;     __device__ __forceinline__ void operator()(const f32x4 (&acc)[2][2][4][2], const pg8::Unit& u, int wr, int wc, int fr, int fq) const {
;     ...
;                     const size_t off = (size_t)row * 1024 + c0 + bj * 128;
;                     f32x4 x0, x1;
;                     if (xin) { x0 = *(const f32x4*)(xin + off); x1 = *(const f32x4*)(xin + off + 4); }
;                     else { const v4u xv = *(const v4u*)(xb + off); x0 = (f32x4){bflo(xv.x), bfhi(xv.x), bflo(xv.y), bfhi(xv.y)}; x1 = (f32x4){bflo(xv.z), bfhi(xv.z), bflo(xv.w), bfhi(xv.w)}; }
.LBB0_1388:
	s_and_b64 vcc, exec, s[8:9]
	s_cbranch_vccnz .LBB0_1514
	global_load_dwordx4 v[130:133], v[180:181], off offset:528 nt
	global_load_dwordx4 v[134:137], v[180:181], off offset:512 nt
	v_or_b32_e32 v178, 0x80, v178
	v_lshl_add_u64 v[178:179], v[178:179], 1, s[54:55]
	s_cbranch_execnz .LBB0_1391

; __device__ __forceinline__ float bflo(unsigned u) { return __uint_as_float(u << 16); }
; __device__ __forceinline__ float bfhi(unsigned u) { return __uint_as_float(u & 0xffff0000u); }
;     __device__ __forceinline__ void operator()(const f32x4 (&acc)[2][2][4][2], const pg8::Unit& u, int wr, int wc, int fr, int fq) const {
;     ...
;                     const size_t off = (size_t)row * 1024 + c0 + bj * 128;
;                     f32x4 x0, x1;
;                     if (xin) { x0 = *(const f32x4*)(xin + off); x1 = *(const f32x4*)(xin + off + 4); }
;                     else { const v4u xv = *(const v4u*)(xb + off); x0 = (f32x4){bflo(xv.x), bfhi(xv.x), bflo(xv.y), bfhi(xv.y)}; x1 = (f32x4){bflo(xv.z), bfhi(xv.z), bflo(xv.w), bfhi(xv.w)}; }
.LBB0_1398:
	v_or_b32_e32 v122, 16, v176
	v_ashrrev_i32_e32 v123, 31, v122
	s_waitcnt lgkmcnt(0)
	v_lshlrev_b64 v[114:115], 10, v[122:123]
	v_lshl_add_u64 v[124:125], v[114:115], 0, v[174:175]
	s_and_b64 vcc, exec, s[8:9]
	v_lshl_add_u64 v[128:129], v[124:125], 2, s[14:15]
	s_cbranch_vccnz .LBB0_1516
	global_load_dwordx4 v[114:117], v[128:129], off offset:16 nt
	global_load_dwordx4 v[118:121], v[128:129], off nt
	v_lshl_add_u64 v[130:131], v[124:125], 1, s[54:55]
	s_cbranch_execnz .LBB0_1401

; __device__ __forceinline__ float bflo(unsigned u) { return __uint_as_float(u << 16); }
; __device__ __forceinline__ float bfhi(unsigned u) { return __uint_as_float(u & 0xffff0000u); }
;     __device__ __forceinline__ void operator()(const f32x4 (&acc)[2][2][4][2], const pg8::Unit& u, int wr, int wc, int fr, int fq) const {
;     ...
;                     const size_t off = (size_t)row * 1024 + c0 + bj * 128;
;                     f32x4 x0, x1;
;                     if (xin) { x0 = *(const f32x4*)(xin + off); x1 = *(const f32x4*)(xin + off + 4); }
;                     else { const v4u xv = *(const v4u*)(xb + off); x0 = (f32x4){bflo(xv.x), bfhi(xv.x), bflo(xv.y), bfhi(xv.y)}; x1 = (f32x4){bflo(xv.z), bfhi(xv.z), bflo(xv.w), bfhi(xv.w)}; }
.LBB0_1404:
	s_and_b64 vcc, exec, s[8:9]
	s_cbranch_vccnz .LBB0_1518
	global_load_dwordx4 v[114:117], v[128:129], off offset:528 nt
	global_load_dwordx4 v[118:121], v[128:129], off offset:512 nt
	v_or_b32_e32 v124, 0x80, v124
	v_lshl_add_u64 v[124:125], v[124:125], 1, s[54:55]
	s_cbranch_execnz .LBB0_1407

; __device__ __forceinline__ float bflo(unsigned u) { return __uint_as_float(u << 16); }
; __device__ __forceinline__ float bfhi(unsigned u) { return __uint_as_float(u & 0xffff0000u); }
;     __device__ __forceinline__ void operator()(const f32x4 (&acc)[2][2][4][2], const pg8::Unit& u, int wr, int wc, int fr, int fq) const {
;     ...
;                     const size_t off = (size_t)row * 1024 + c0 + bj * 128;
;                     f32x4 x0, x1;
;                     if (xin) { x0 = *(const f32x4*)(xin + off); x1 = *(const f32x4*)(xin + off + 4); }
;                     else { const v4u xv = *(const v4u*)(xb + off); x0 = (f32x4){bflo(xv.x), bfhi(xv.x), bflo(xv.y), bfhi(xv.y)}; x1 = (f32x4){bflo(xv.z), bfhi(xv.z), bflo(xv.w), bfhi(xv.w)}; }
.LBB0_1414:
	v_or_b32_e32 v106, 32, v176
	v_ashrrev_i32_e32 v107, 31, v106
	s_waitcnt lgkmcnt(0)
	v_lshlrev_b64 v[98:99], 10, v[106:107]
	v_lshl_add_u64 v[108:109], v[98:99], 0, v[174:175]
	s_and_b64 vcc, exec, s[8:9]
	v_lshl_add_u64 v[112:113], v[108:109], 2, s[14:15]
	s_cbranch_vccnz .LBB0_1520
	global_load_dwordx4 v[98:101], v[112:113], off offset:16 nt
	global_load_dwordx4 v[102:105], v[112:113], off nt
	v_lshl_add_u64 v[114:115], v[108:109], 1, s[54:55]
	s_cbranch_execnz .LBB0_1417

; __device__ __forceinline__ float bflo(unsigned u) { return __uint_as_float(u << 16); }
; __device__ __forceinline__ float bfhi(unsigned u) { return __uint_as_float(u & 0xffff0000u); }
;     __device__ __forceinline__ void operator()(const f32x4 (&acc)[2][2][4][2], const pg8::Unit& u, int wr, int wc, int fr, int fq) const {
;     ...
;                     const size_t off = (size_t)row * 1024 + c0 + bj * 128;
;                     f32x4 x0, x1;
;                     if (xin) { x0 = *(const f32x4*)(xin + off); x1 = *(const f32x4*)(xin + off + 4); }
;                     else { const v4u xv = *(const v4u*)(xb + off); x0 = (f32x4){bflo(xv.x), bfhi(xv.x), bflo(xv.y), bfhi(xv.y)}; x1 = (f32x4){bflo(xv.z), bfhi(xv.z), bflo(xv.w), bfhi(xv.w)}; }
.LBB0_1420:
	s_and_b64 vcc, exec, s[8:9]
	s_cbranch_vccnz .LBB0_1522
	global_load_dwordx4 v[98:101], v[112:113], off offset:528 nt
	global_load_dwordx4 v[102:105], v[112:113], off offset:512 nt
	v_or_b32_e32 v108, 0x80, v108
	v_lshl_add_u64 v[108:109], v[108:109], 1, s[54:55]
	s_cbranch_execnz .LBB0_1423

; __device__ __forceinline__ float bflo(unsigned u) { return __uint_as_float(u << 16); }
; __device__ __forceinline__ float bfhi(unsigned u) { return __uint_as_float(u & 0xffff0000u); }
;     __device__ __forceinline__ void operator()(const f32x4 (&acc)[2][2][4][2], const pg8::Unit& u, int wr, int wc, int fr, int fq) const {
;     ...
;                     const size_t off = (size_t)row * 1024 + c0 + bj * 128;
;                     f32x4 x0, x1;
;                     if (xin) { x0 = *(const f32x4*)(xin + off); x1 = *(const f32x4*)(xin + off + 4); }
;                     else { const v4u xv = *(const v4u*)(xb + off); x0 = (f32x4){bflo(xv.x), bfhi(xv.x), bflo(xv.y), bfhi(xv.y)}; x1 = (f32x4){bflo(xv.z), bfhi(xv.z), bflo(xv.w), bfhi(xv.w)}; }
.LBB0_1430:
	v_or_b32_e32 v90, 48, v176
	v_ashrrev_i32_e32 v91, 31, v90
	s_waitcnt lgkmcnt(0)
	v_lshlrev_b64 v[82:83], 10, v[90:91]
	v_lshl_add_u64 v[92:93], v[82:83], 0, v[174:175]
	s_and_b64 vcc, exec, s[8:9]
	v_lshl_add_u64 v[96:97], v[92:93], 2, s[14:15]
	s_cbranch_vccnz .LBB0_1524
	global_load_dwordx4 v[82:85], v[96:97], off offset:16 nt
	global_load_dwordx4 v[86:89], v[96:97], off nt
	v_lshl_add_u64 v[98:99], v[92:93], 1, s[54:55]
	s_cbranch_execnz .LBB0_1433

; __device__ __forceinline__ float bflo(unsigned u) { return __uint_as_float(u << 16); }
; __device__ __forceinline__ float bfhi(unsigned u) { return __uint_as_float(u & 0xffff0000u); }
;     __device__ __forceinline__ void operator()(const f32x4 (&acc)[2][2][4][2], const pg8::Unit& u, int wr, int wc, int fr, int fq) const {
;     ...
;                     const size_t off = (size_t)row * 1024 + c0 + bj * 128;
;                     f32x4 x0, x1;
;                     if (xin) { x0 = *(const f32x4*)(xin + off); x1 = *(const f32x4*)(xin + off + 4); }
;                     else { const v4u xv = *(const v4u*)(xb + off); x0 = (f32x4){bflo(xv.x), bfhi(xv.x), bflo(xv.y), bfhi(xv.y)}; x1 = (f32x4){bflo(xv.z), bfhi(xv.z), bflo(xv.w), bfhi(xv.w)}; }
.LBB0_1436:
	s_and_b64 vcc, exec, s[8:9]
	s_cbranch_vccnz .LBB0_1526
	global_load_dwordx4 v[82:85], v[96:97], off offset:528 nt
	global_load_dwordx4 v[86:89], v[96:97], off offset:512 nt
	v_or_b32_e32 v92, 0x80, v92
	v_lshl_add_u64 v[92:93], v[92:93], 1, s[54:55]
	s_cbranch_execnz .LBB0_1439

; __device__ __forceinline__ float bflo(unsigned u) { return __uint_as_float(u << 16); }
; __device__ __forceinline__ float bfhi(unsigned u) { return __uint_as_float(u & 0xffff0000u); }
;     __device__ __forceinline__ void operator()(const f32x4 (&acc)[2][2][4][2], const pg8::Unit& u, int wr, int wc, int fr, int fq) const {
;     ...
;                     const size_t off = (size_t)row * 1024 + c0 + bj * 128;
;                     f32x4 x0, x1;
;                     if (xin) { x0 = *(const f32x4*)(xin + off); x1 = *(const f32x4*)(xin + off + 4); }
;                     else { const v4u xv = *(const v4u*)(xb + off); x0 = (f32x4){bflo(xv.x), bfhi(xv.x), bflo(xv.y), bfhi(xv.y)}; x1 = (f32x4){bflo(xv.z), bfhi(xv.z), bflo(xv.w), bfhi(xv.w)}; }
.LBB0_1446:
	v_add_u32_e32 v74, 0x80, v176
	v_ashrrev_i32_e32 v75, 31, v74
	s_waitcnt lgkmcnt(0)
	v_lshlrev_b64 v[66:67], 10, v[74:75]
	v_lshl_add_u64 v[76:77], v[66:67], 0, v[174:175]
	s_and_b64 vcc, exec, s[8:9]
	v_lshl_add_u64 v[80:81], v[76:77], 2, s[14:15]
	s_cbranch_vccnz .LBB0_1528
	global_load_dwordx4 v[66:69], v[80:81], off offset:16 nt
	global_load_dwordx4 v[70:73], v[80:81], off nt
	v_lshl_add_u64 v[82:83], v[76:77], 1, s[54:55]
	s_cbranch_execnz .LBB0_1449

; __device__ __forceinline__ float bflo(unsigned u) { return __uint_as_float(u << 16); }
; __device__ __forceinline__ float bfhi(unsigned u) { return __uint_as_float(u & 0xffff0000u); }
;     __device__ __forceinline__ void operator()(const f32x4 (&acc)[2][2][4][2], const pg8::Unit& u, int wr, int wc, int fr, int fq) const {
;     ...
;                     const size_t off = (size_t)row * 1024 + c0 + bj * 128;
;                     f32x4 x0, x1;
;                     if (xin) { x0 = *(const f32x4*)(xin + off); x1 = *(const f32x4*)(xin + off + 4); }
;                     else { const v4u xv = *(const v4u*)(xb + off); x0 = (f32x4){bflo(xv.x), bfhi(xv.x), bflo(xv.y), bfhi(xv.y)}; x1 = (f32x4){bflo(xv.z), bfhi(xv.z), bflo(xv.w), bfhi(xv.w)}; }
.LBB0_1452:
	s_and_b64 vcc, exec, s[8:9]
	s_cbranch_vccnz .LBB0_1530
	global_load_dwordx4 v[66:69], v[80:81], off offset:528 nt
	global_load_dwordx4 v[70:73], v[80:81], off offset:512 nt
	v_or_b32_e32 v76, 0x80, v76
	v_lshl_add_u64 v[76:77], v[76:77], 1, s[54:55]
	s_cbranch_execnz .LBB0_1455

; __device__ __forceinline__ float bflo(unsigned u) { return __uint_as_float(u << 16); }
; __device__ __forceinline__ float bfhi(unsigned u) { return __uint_as_float(u & 0xffff0000u); }
;     __device__ __forceinline__ void operator()(const f32x4 (&acc)[2][2][4][2], const pg8::Unit& u, int wr, int wc, int fr, int fq) const {
;     ...
;                     const size_t off = (size_t)row * 1024 + c0 + bj * 128;
;                     f32x4 x0, x1;
;                     if (xin) { x0 = *(const f32x4*)(xin + off); x1 = *(const f32x4*)(xin + off + 4); }
;                     else { const v4u xv = *(const v4u*)(xb + off); x0 = (f32x4){bflo(xv.x), bfhi(xv.x), bflo(xv.y), bfhi(xv.y)}; x1 = (f32x4){bflo(xv.z), bfhi(xv.z), bflo(xv.w), bfhi(xv.w)}; }
.LBB0_1462:
	v_add_u32_e32 v58, 0x90, v176
	v_ashrrev_i32_e32 v59, 31, v58
	s_waitcnt lgkmcnt(0)
	v_lshlrev_b64 v[50:51], 10, v[58:59]
	v_lshl_add_u64 v[60:61], v[50:51], 0, v[174:175]
	s_and_b64 vcc, exec, s[8:9]
	v_lshl_add_u64 v[64:65], v[60:61], 2, s[14:15]
	s_cbranch_vccnz .LBB0_1532
	global_load_dwordx4 v[50:53], v[64:65], off offset:16 nt
	global_load_dwordx4 v[54:57], v[64:65], off nt
	v_lshl_add_u64 v[66:67], v[60:61], 1, s[54:55]
	s_cbranch_execnz .LBB0_1465

; __device__ __forceinline__ float bflo(unsigned u) { return __uint_as_float(u << 16); }
; __device__ __forceinline__ float bfhi(unsigned u) { return __uint_as_float(u & 0xffff0000u); }
;     __device__ __forceinline__ void operator()(const f32x4 (&acc)[2][2][4][2], const pg8::Unit& u, int wr, int wc, int fr, int fq) const {
;     ...
;                     const size_t off = (size_t)row * 1024 + c0 + bj * 128;
;                     f32x4 x0, x1;
;                     if (xin) { x0 = *(const f32x4*)(xin + off); x1 = *(const f32x4*)(xin + off + 4); }
;                     else { const v4u xv = *(const v4u*)(xb + off); x0 = (f32x4){bflo(xv.x), bfhi(xv.x), bflo(xv.y), bfhi(xv.y)}; x1 = (f32x4){bflo(xv.z), bfhi(xv.z), bflo(xv.w), bfhi(xv.w)}; }
.LBB0_1468:
	s_and_b64 vcc, exec, s[8:9]
	s_cbranch_vccnz .LBB0_1534
	global_load_dwordx4 v[50:53], v[64:65], off offset:528 nt
	global_load_dwordx4 v[54:57], v[64:65], off offset:512 nt
	v_or_b32_e32 v60, 0x80, v60
	v_lshl_add_u64 v[60:61], v[60:61], 1, s[54:55]
	s_cbranch_execnz .LBB0_1471

; __device__ __forceinline__ float bflo(unsigned u) { return __uint_as_float(u << 16); }
; __device__ __forceinline__ float bfhi(unsigned u) { return __uint_as_float(u & 0xffff0000u); }
;     __device__ __forceinline__ void operator()(const f32x4 (&acc)[2][2][4][2], const pg8::Unit& u, int wr, int wc, int fr, int fq) const {
;     ...
;                     const size_t off = (size_t)row * 1024 + c0 + bj * 128;
;                     f32x4 x0, x1;
;                     if (xin) { x0 = *(const f32x4*)(xin + off); x1 = *(const f32x4*)(xin + off + 4); }
;                     else { const v4u xv = *(const v4u*)(xb + off); x0 = (f32x4){bflo(xv.x), bfhi(xv.x), bflo(xv.y), bfhi(xv.y)}; x1 = (f32x4){bflo(xv.z), bfhi(xv.z), bflo(xv.w), bfhi(xv.w)}; }
.LBB0_1478:
	v_add_u32_e32 v42, 0xa0, v176
	v_ashrrev_i32_e32 v43, 31, v42
	s_waitcnt lgkmcnt(0)
	v_lshlrev_b64 v[34:35], 10, v[42:43]
	v_lshl_add_u64 v[44:45], v[34:35], 0, v[174:175]
	s_and_b64 vcc, exec, s[8:9]
	v_lshl_add_u64 v[48:49], v[44:45], 2, s[14:15]
	s_cbranch_vccnz .LBB0_1536
	global_load_dwordx4 v[34:37], v[48:49], off offset:16 nt
	global_load_dwordx4 v[38:41], v[48:49], off nt
	v_lshl_add_u64 v[50:51], v[44:45], 1, s[54:55]
	s_cbranch_execnz .LBB0_1481

; __device__ __forceinline__ float bflo(unsigned u) { return __uint_as_float(u << 16); }
; __device__ __forceinline__ float bfhi(unsigned u) { return __uint_as_float(u & 0xffff0000u); }
;     __device__ __forceinline__ void operator()(const f32x4 (&acc)[2][2][4][2], const pg8::Unit& u, int wr, int wc, int fr, int fq) const {
;     ...
;                     const size_t off = (size_t)row * 1024 + c0 + bj * 128;
;                     f32x4 x0, x1;
;                     if (xin) { x0 = *(const f32x4*)(xin + off); x1 = *(const f32x4*)(xin + off + 4); }
;                     else { const v4u xv = *(const v4u*)(xb + off); x0 = (f32x4){bflo(xv.x), bfhi(xv.x), bflo(xv.y), bfhi(xv.y)}; x1 = (f32x4){bflo(xv.z), bfhi(xv.z), bflo(xv.w), bfhi(xv.w)}; }
.LBB0_1484:
	s_and_b64 vcc, exec, s[8:9]
	s_cbranch_vccnz .LBB0_1538
	global_load_dwordx4 v[34:37], v[48:49], off offset:528 nt
	global_load_dwordx4 v[38:41], v[48:49], off offset:512 nt
	v_or_b32_e32 v44, 0x80, v44
	v_lshl_add_u64 v[44:45], v[44:45], 1, s[54:55]
	s_cbranch_execnz .LBB0_1487

; __device__ __forceinline__ float bflo(unsigned u) { return __uint_as_float(u << 16); }
; __device__ __forceinline__ float bfhi(unsigned u) { return __uint_as_float(u & 0xffff0000u); }
;     __device__ __forceinline__ void operator()(const f32x4 (&acc)[2][2][4][2], const pg8::Unit& u, int wr, int wc, int fr, int fq) const {
;     ...
;                     const size_t off = (size_t)row * 1024 + c0 + bj * 128;
;                     f32x4 x0, x1;
;                     if (xin) { x0 = *(const f32x4*)(xin + off); x1 = *(const f32x4*)(xin + off + 4); }
;                     else { const v4u xv = *(const v4u*)(xb + off); x0 = (f32x4){bflo(xv.x), bfhi(xv.x), bflo(xv.y), bfhi(xv.y)}; x1 = (f32x4){bflo(xv.z), bfhi(xv.z), bflo(xv.w), bfhi(xv.w)}; }
.LBB0_1494:
	v_add_u32_e32 v26, 0xb0, v176
	v_ashrrev_i32_e32 v27, 31, v26
	s_waitcnt lgkmcnt(0)
	v_lshlrev_b64 v[18:19], 10, v[26:27]
	v_lshl_add_u64 v[28:29], v[18:19], 0, v[174:175]
	s_and_b64 vcc, exec, s[8:9]
	v_lshl_add_u64 v[32:33], v[28:29], 2, s[14:15]
	s_cbranch_vccnz .LBB0_1540
	global_load_dwordx4 v[18:21], v[32:33], off offset:16 nt
	global_load_dwordx4 v[22:25], v[32:33], off nt
	v_lshl_add_u64 v[34:35], v[28:29], 1, s[54:55]
	s_cbranch_execnz .LBB0_1497

; __device__ __forceinline__ float bflo(unsigned u) { return __uint_as_float(u << 16); }
; __device__ __forceinline__ float bfhi(unsigned u) { return __uint_as_float(u & 0xffff0000u); }
;     __device__ __forceinline__ void operator()(const f32x4 (&acc)[2][2][4][2], const pg8::Unit& u, int wr, int wc, int fr, int fq) const {
;     ...
;                     const size_t off = (size_t)row * 1024 + c0 + bj * 128;
;                     f32x4 x0, x1;
;                     if (xin) { x0 = *(const f32x4*)(xin + off); x1 = *(const f32x4*)(xin + off + 4); }
;                     else { const v4u xv = *(const v4u*)(xb + off); x0 = (f32x4){bflo(xv.x), bfhi(xv.x), bflo(xv.y), bfhi(xv.y)}; x1 = (f32x4){bflo(xv.z), bfhi(xv.z), bflo(xv.w), bfhi(xv.w)}; }
.LBB0_1500:
	s_and_b64 vcc, exec, s[8:9]
	s_cbranch_vccnz .LBB0_1542
	global_load_dwordx4 v[18:21], v[32:33], off offset:528 nt
	global_load_dwordx4 v[22:25], v[32:33], off offset:512 nt
	v_or_b32_e32 v28, 0x80, v28
	v_lshl_add_u64 v[28:29], v[28:29], 1, s[54:55]
	s_cbranch_execnz .LBB0_1503
